# tail conversion stores write-through sc1 (avoid L2 pollution)
# speedup vs baseline: 1.0040x; 1.0040x over previous
.Ltail_gk_A:
	v_mul_f32_e32 v217, v96, v213
	v_mul_f32_e32 v6, v6, v217
	v_mul_f32_e32 v7, v7, v217
	v_mul_f32_e32 v8, v8, v217
	v_mul_f32_e32 v9, v9, v217
	ds_write_b32 v205, v6 offset:0
	ds_write_b32 v205, v7 offset:4
	ds_write_b32 v205, v8 offset:8
	ds_write_b32 v205, v9 offset:12
	v_mul_f32_e32 v217, v97, v213
	v_mul_f32_e32 v10, v10, v217
	v_mul_f32_e32 v11, v11, v217
	v_mul_f32_e32 v12, v12, v217
	v_mul_f32_e32 v13, v13, v217
	ds_write_b32 v205, v10 offset:1056
	ds_write_b32 v205, v11 offset:1060
	ds_write_b32 v205, v12 offset:1064
	ds_write_b32 v205, v13 offset:1068
	v_mul_f32_e32 v217, v98, v213
	v_mul_f32_e32 v14, v14, v217
	v_mul_f32_e32 v15, v15, v217
	v_mul_f32_e32 v16, v16, v217
	v_mul_f32_e32 v17, v17, v217
	ds_write_b32 v205, v14 offset:2112
	ds_write_b32 v205, v15 offset:2116
	ds_write_b32 v205, v16 offset:2120
	ds_write_b32 v205, v17 offset:2124
	v_mul_f32_e32 v217, v99, v213
	v_mul_f32_e32 v18, v18, v217
	v_mul_f32_e32 v19, v19, v217
	v_mul_f32_e32 v20, v20, v217
	v_mul_f32_e32 v21, v21, v217
	ds_write_b32 v205, v18 offset:3168
	ds_write_b32 v205, v19 offset:3172
	ds_write_b32 v205, v20 offset:3176
	ds_write_b32 v205, v21 offset:3180
	v_mul_f32_e32 v217, v100, v213
	v_mul_f32_e32 v22, v22, v217
	v_mul_f32_e32 v23, v23, v217
	v_mul_f32_e32 v24, v24, v217
	v_mul_f32_e32 v25, v25, v217
	ds_write_b32 v205, v22 offset:4224
	ds_write_b32 v205, v23 offset:4228
	ds_write_b32 v205, v24 offset:4232
	ds_write_b32 v205, v25 offset:4236
	v_mul_f32_e32 v217, v101, v213
	v_mul_f32_e32 v26, v26, v217
	v_mul_f32_e32 v27, v27, v217
	v_mul_f32_e32 v28, v28, v217
	v_mul_f32_e32 v29, v29, v217
	ds_write_b32 v205, v26 offset:5280
	ds_write_b32 v205, v27 offset:5284
	ds_write_b32 v205, v28 offset:5288
	ds_write_b32 v205, v29 offset:5292
	v_mul_f32_e32 v217, v102, v213
	v_mul_f32_e32 v30, v30, v217
	v_mul_f32_e32 v31, v31, v217
	v_mul_f32_e32 v32, v32, v217
	v_mul_f32_e32 v33, v33, v217
	ds_write_b32 v205, v30 offset:6336
	ds_write_b32 v205, v31 offset:6340
	ds_write_b32 v205, v32 offset:6344
	ds_write_b32 v205, v33 offset:6348
	v_mul_f32_e32 v217, v103, v213
	v_mul_f32_e32 v34, v34, v217
	v_mul_f32_e32 v35, v35, v217
	v_mul_f32_e32 v36, v36, v217
	v_mul_f32_e32 v37, v37, v217
	ds_write_b32 v205, v34 offset:7392
	ds_write_b32 v205, v35 offset:7396
	ds_write_b32 v205, v36 offset:7400
	ds_write_b32 v205, v37 offset:7404
	s_waitcnt lgkmcnt(0)
	ds_read2_b32 v[144:145], v206 offset0:0 offset1:33
	ds_read2_b32 v[146:147], v206 offset0:66 offset1:99
	ds_read2_b32 v[148:149], v206 offset0:132 offset1:165
	ds_read2_b32 v[150:151], v206 offset0:198 offset1:231
	s_waitcnt lgkmcnt(3)
	v_cvt_pk_bf16_f32 v152, v144, v145
	s_waitcnt lgkmcnt(2)
	v_cvt_pk_bf16_f32 v153, v146, v147
	s_waitcnt lgkmcnt(1)
	v_cvt_pk_bf16_f32 v154, v148, v149
	s_waitcnt lgkmcnt(0)
	v_cvt_pk_bf16_f32 v155, v150, v151
	s_mov_b64 s[6:7], s[48:49]
	global_store_dwordx4 v214, v[152:155], s[6:7] sc1
	ds_read2_b32 v[144:145], v206 offset0:8 offset1:41
	ds_read2_b32 v[146:147], v206 offset0:74 offset1:107
	ds_read2_b32 v[148:149], v206 offset0:140 offset1:173
	ds_read2_b32 v[150:151], v206 offset0:206 offset1:239
	s_waitcnt lgkmcnt(3)
	v_cvt_pk_bf16_f32 v156, v144, v145
	s_waitcnt lgkmcnt(2)
	v_cvt_pk_bf16_f32 v157, v146, v147
	s_waitcnt lgkmcnt(1)
	v_cvt_pk_bf16_f32 v158, v148, v149
	s_waitcnt lgkmcnt(0)
	v_cvt_pk_bf16_f32 v159, v150, v151
	s_add_u32 s6, s6, 0x8000
	s_addc_u32 s7, s7, 0
	global_store_dwordx4 v214, v[156:159], s[6:7] sc1
	ds_read2_b32 v[144:145], v206 offset0:16 offset1:49
	ds_read2_b32 v[146:147], v206 offset0:82 offset1:115
	ds_read2_b32 v[148:149], v206 offset0:148 offset1:181
	ds_read2_b32 v[150:151], v206 offset0:214 offset1:247
	s_waitcnt lgkmcnt(3)
	v_cvt_pk_bf16_f32 v152, v144, v145
	s_waitcnt lgkmcnt(2)
	v_cvt_pk_bf16_f32 v153, v146, v147
	s_waitcnt lgkmcnt(1)
	v_cvt_pk_bf16_f32 v154, v148, v149
	s_waitcnt lgkmcnt(0)
	v_cvt_pk_bf16_f32 v155, v150, v151
	s_add_u32 s6, s6, 0x8000
	s_addc_u32 s7, s7, 0
	global_store_dwordx4 v214, v[152:155], s[6:7] sc1
	ds_read2_b32 v[144:145], v206 offset0:24 offset1:57
	ds_read2_b32 v[146:147], v206 offset0:90 offset1:123
	ds_read2_b32 v[148:149], v206 offset0:156 offset1:189
	ds_read2_b32 v[150:151], v206 offset0:222 offset1:255
	s_waitcnt lgkmcnt(3)
	v_cvt_pk_bf16_f32 v156, v144, v145
	s_waitcnt lgkmcnt(2)
	v_cvt_pk_bf16_f32 v157, v146, v147
	s_waitcnt lgkmcnt(1)
	v_cvt_pk_bf16_f32 v158, v148, v149
	s_waitcnt lgkmcnt(0)
	v_cvt_pk_bf16_f32 v159, v150, v151
	s_add_u32 s6, s6, 0x8000
	s_addc_u32 s7, s7, 0
	global_store_dwordx4 v214, v[156:159], s[6:7] sc1
	s_cmp_eq_u32 s52, 0
	s_cbranch_scc1 .Ltail_end
	s_sub_u32 s52, s52, 1
	s_add_u32 s70, s70, s71
	s_cmp_lt_u32 s70, 0x2520
	s_cbranch_scc0 .Ltail_ni_r1
	s_cmp_lt_u32 s70, 0x1d20
	s_cbranch_scc0 .Ltail_m0_r1
	s_mul_hi_u32 s54, s70, 0x1194539
	s_mul_i32 s4, s54, 0xe9
	s_sub_u32 s55, s70, s4
	s_mov_b32 s46, 1
	s_movk_i32 s78, 0x7460
	s_mov_b64 s[56:57], s[64:65]
	s_mov_b64 s[48:49], s[66:67]
	s_branch .Ltail_cm_r1

.Ltail_gk_B:
	v_mul_f32_e32 v217, v104, v215
	v_mul_f32_e32 v38, v38, v217
	v_mul_f32_e32 v39, v39, v217
	v_mul_f32_e32 v40, v40, v217
	v_mul_f32_e32 v41, v41, v217
	ds_write_b32 v205, v38 offset:0
	ds_write_b32 v205, v39 offset:4
	ds_write_b32 v205, v40 offset:8
	ds_write_b32 v205, v41 offset:12
	v_mul_f32_e32 v217, v105, v215
	v_mul_f32_e32 v42, v42, v217
	v_mul_f32_e32 v43, v43, v217
	v_mul_f32_e32 v44, v44, v217
	v_mul_f32_e32 v45, v45, v217
	ds_write_b32 v205, v42 offset:1056
	ds_write_b32 v205, v43 offset:1060
	ds_write_b32 v205, v44 offset:1064
	ds_write_b32 v205, v45 offset:1068
	v_mul_f32_e32 v217, v106, v215
	v_mul_f32_e32 v46, v46, v217
	v_mul_f32_e32 v47, v47, v217
	v_mul_f32_e32 v48, v48, v217
	v_mul_f32_e32 v49, v49, v217
	ds_write_b32 v205, v46 offset:2112
	ds_write_b32 v205, v47 offset:2116
	ds_write_b32 v205, v48 offset:2120
	ds_write_b32 v205, v49 offset:2124
	v_mul_f32_e32 v217, v107, v215
	v_mul_f32_e32 v58, v58, v217
	v_mul_f32_e32 v59, v59, v217
	v_mul_f32_e32 v60, v60, v217
	v_mul_f32_e32 v61, v61, v217
	ds_write_b32 v205, v58 offset:3168
	ds_write_b32 v205, v59 offset:3172
	ds_write_b32 v205, v60 offset:3176
	ds_write_b32 v205, v61 offset:3180
	v_mul_f32_e32 v217, v108, v215
	v_mul_f32_e32 v62, v62, v217
	v_mul_f32_e32 v63, v63, v217
	v_mul_f32_e32 v64, v64, v217
	v_mul_f32_e32 v65, v65, v217
	ds_write_b32 v205, v62 offset:4224
	ds_write_b32 v205, v63 offset:4228
	ds_write_b32 v205, v64 offset:4232
	ds_write_b32 v205, v65 offset:4236
	v_mul_f32_e32 v217, v109, v215
	v_mul_f32_e32 v66, v66, v217
	v_mul_f32_e32 v67, v67, v217
	v_mul_f32_e32 v68, v68, v217
	v_mul_f32_e32 v69, v69, v217
	ds_write_b32 v205, v66 offset:5280
	ds_write_b32 v205, v67 offset:5284
	ds_write_b32 v205, v68 offset:5288
	ds_write_b32 v205, v69 offset:5292
	v_mul_f32_e32 v217, v110, v215
	v_mul_f32_e32 v88, v88, v217
	v_mul_f32_e32 v89, v89, v217
	v_mul_f32_e32 v90, v90, v217
	v_mul_f32_e32 v91, v91, v217
	ds_write_b32 v205, v88 offset:6336
	ds_write_b32 v205, v89 offset:6340
	ds_write_b32 v205, v90 offset:6344
	ds_write_b32 v205, v91 offset:6348
	v_mul_f32_e32 v217, v111, v215
	v_mul_f32_e32 v92, v92, v217
	v_mul_f32_e32 v93, v93, v217
	v_mul_f32_e32 v94, v94, v217
	v_mul_f32_e32 v95, v95, v217
	ds_write_b32 v205, v92 offset:7392
	ds_write_b32 v205, v93 offset:7396
	ds_write_b32 v205, v94 offset:7400
	ds_write_b32 v205, v95 offset:7404
	s_waitcnt lgkmcnt(0)
	ds_read2_b32 v[144:145], v206 offset0:0 offset1:33
	ds_read2_b32 v[146:147], v206 offset0:66 offset1:99
	ds_read2_b32 v[148:149], v206 offset0:132 offset1:165
	ds_read2_b32 v[150:151], v206 offset0:198 offset1:231
	s_waitcnt lgkmcnt(3)
	v_cvt_pk_bf16_f32 v152, v144, v145
	s_waitcnt lgkmcnt(2)
	v_cvt_pk_bf16_f32 v153, v146, v147
	s_waitcnt lgkmcnt(1)
	v_cvt_pk_bf16_f32 v154, v148, v149
	s_waitcnt lgkmcnt(0)
	v_cvt_pk_bf16_f32 v155, v150, v151
	s_mov_b64 s[6:7], s[50:51]
	global_store_dwordx4 v216, v[152:155], s[6:7] sc1
	ds_read2_b32 v[144:145], v206 offset0:8 offset1:41
	ds_read2_b32 v[146:147], v206 offset0:74 offset1:107
	ds_read2_b32 v[148:149], v206 offset0:140 offset1:173
	ds_read2_b32 v[150:151], v206 offset0:206 offset1:239
	s_waitcnt lgkmcnt(3)
	v_cvt_pk_bf16_f32 v156, v144, v145
	s_waitcnt lgkmcnt(2)
	v_cvt_pk_bf16_f32 v157, v146, v147
	s_waitcnt lgkmcnt(1)
	v_cvt_pk_bf16_f32 v158, v148, v149
	s_waitcnt lgkmcnt(0)
	v_cvt_pk_bf16_f32 v159, v150, v151
	s_add_u32 s6, s6, 0x8000
	s_addc_u32 s7, s7, 0
	global_store_dwordx4 v216, v[156:159], s[6:7] sc1
	ds_read2_b32 v[144:145], v206 offset0:16 offset1:49
	ds_read2_b32 v[146:147], v206 offset0:82 offset1:115
	ds_read2_b32 v[148:149], v206 offset0:148 offset1:181
	ds_read2_b32 v[150:151], v206 offset0:214 offset1:247
	s_waitcnt lgkmcnt(3)
	v_cvt_pk_bf16_f32 v152, v144, v145
	s_waitcnt lgkmcnt(2)
	v_cvt_pk_bf16_f32 v153, v146, v147
	s_waitcnt lgkmcnt(1)
	v_cvt_pk_bf16_f32 v154, v148, v149
	s_waitcnt lgkmcnt(0)
	v_cvt_pk_bf16_f32 v155, v150, v151
	s_add_u32 s6, s6, 0x8000
	s_addc_u32 s7, s7, 0
	global_store_dwordx4 v216, v[152:155], s[6:7] sc1
	ds_read2_b32 v[144:145], v206 offset0:24 offset1:57
	ds_read2_b32 v[146:147], v206 offset0:90 offset1:123
	ds_read2_b32 v[148:149], v206 offset0:156 offset1:189
	ds_read2_b32 v[150:151], v206 offset0:222 offset1:255
	s_waitcnt lgkmcnt(3)
	v_cvt_pk_bf16_f32 v156, v144, v145
	s_waitcnt lgkmcnt(2)
	v_cvt_pk_bf16_f32 v157, v146, v147
	s_waitcnt lgkmcnt(1)
	v_cvt_pk_bf16_f32 v158, v148, v149
	s_waitcnt lgkmcnt(0)
	v_cvt_pk_bf16_f32 v159, v150, v151
	s_add_u32 s6, s6, 0x8000
	s_addc_u32 s7, s7, 0
	global_store_dwordx4 v216, v[156:159], s[6:7] sc1
	s_cmp_eq_u32 s52, 0
	s_cbranch_scc1 .Ltail_end
	s_sub_u32 s52, s52, 1
	s_add_u32 s70, s70, s71
	s_cmp_lt_u32 s70, 0x2520
	s_cbranch_scc0 .Ltail_ni_r2
	s_cmp_lt_u32 s70, 0x1d20
	s_cbranch_scc0 .Ltail_m0_r2
	s_mul_hi_u32 s54, s70, 0x1194539
	s_mul_i32 s4, s54, 0xe9
	s_sub_u32 s55, s70, s4
	s_mov_b32 s47, 1
	s_movk_i32 s78, 0x7460
	s_mov_b64 s[56:57], s[64:65]
	s_mov_b64 s[50:51], s[66:67]
	s_branch .Ltail_cm_r2

.Ltail_gk_C:
	v_mul_f32_e32 v217, v240, v248
	v_mul_f32_e32 v178, v178, v217
	v_mul_f32_e32 v179, v179, v217
	v_mul_f32_e32 v180, v180, v217
	v_mul_f32_e32 v181, v181, v217
	ds_write_b32 v205, v178 offset:0
	ds_write_b32 v205, v179 offset:4
	ds_write_b32 v205, v180 offset:8
	ds_write_b32 v205, v181 offset:12
	v_mul_f32_e32 v217, v241, v248
	v_mul_f32_e32 v182, v182, v217
	v_mul_f32_e32 v183, v183, v217
	v_mul_f32_e32 v184, v184, v217
	v_mul_f32_e32 v185, v185, v217
	ds_write_b32 v205, v182 offset:1056
	ds_write_b32 v205, v183 offset:1060
	ds_write_b32 v205, v184 offset:1064
	ds_write_b32 v205, v185 offset:1068
	v_mul_f32_e32 v217, v242, v248
	v_mul_f32_e32 v186, v186, v217
	v_mul_f32_e32 v187, v187, v217
	v_mul_f32_e32 v188, v188, v217
	v_mul_f32_e32 v189, v189, v217
	ds_write_b32 v205, v186 offset:2112
	ds_write_b32 v205, v187 offset:2116
	ds_write_b32 v205, v188 offset:2120
	ds_write_b32 v205, v189 offset:2124
	v_mul_f32_e32 v217, v243, v248
	v_mul_f32_e32 v220, v220, v217
	v_mul_f32_e32 v221, v221, v217
	v_mul_f32_e32 v222, v222, v217
	v_mul_f32_e32 v223, v223, v217
	ds_write_b32 v205, v220 offset:3168
	ds_write_b32 v205, v221 offset:3172
	ds_write_b32 v205, v222 offset:3176
	ds_write_b32 v205, v223 offset:3180
	v_mul_f32_e32 v217, v244, v248
	v_mul_f32_e32 v224, v224, v217
	v_mul_f32_e32 v225, v225, v217
	v_mul_f32_e32 v226, v226, v217
	v_mul_f32_e32 v227, v227, v217
	ds_write_b32 v205, v224 offset:4224
	ds_write_b32 v205, v225 offset:4228
	ds_write_b32 v205, v226 offset:4232
	ds_write_b32 v205, v227 offset:4236
	v_mul_f32_e32 v217, v245, v248
	v_mul_f32_e32 v228, v228, v217
	v_mul_f32_e32 v229, v229, v217
	v_mul_f32_e32 v230, v230, v217
	v_mul_f32_e32 v231, v231, v217
	ds_write_b32 v205, v228 offset:5280
	ds_write_b32 v205, v229 offset:5284
	ds_write_b32 v205, v230 offset:5288
	ds_write_b32 v205, v231 offset:5292
	v_mul_f32_e32 v217, v246, v248
	v_mul_f32_e32 v232, v232, v217
	v_mul_f32_e32 v233, v233, v217
	v_mul_f32_e32 v234, v234, v217
	v_mul_f32_e32 v235, v235, v217
	ds_write_b32 v205, v232 offset:6336
	ds_write_b32 v205, v233 offset:6340
	ds_write_b32 v205, v234 offset:6344
	ds_write_b32 v205, v235 offset:6348
	v_mul_f32_e32 v217, v247, v248
	v_mul_f32_e32 v236, v236, v217
	v_mul_f32_e32 v237, v237, v217
	v_mul_f32_e32 v238, v238, v217
	v_mul_f32_e32 v239, v239, v217
	ds_write_b32 v205, v236 offset:7392
	ds_write_b32 v205, v237 offset:7396
	ds_write_b32 v205, v238 offset:7400
	ds_write_b32 v205, v239 offset:7404
	s_waitcnt lgkmcnt(0)
	ds_read2_b32 v[144:145], v206 offset0:0 offset1:33
	ds_read2_b32 v[146:147], v206 offset0:66 offset1:99
	ds_read2_b32 v[148:149], v206 offset0:132 offset1:165
	ds_read2_b32 v[150:151], v206 offset0:198 offset1:231
	s_waitcnt lgkmcnt(3)
	v_cvt_pk_bf16_f32 v152, v144, v145
	s_waitcnt lgkmcnt(2)
	v_cvt_pk_bf16_f32 v153, v146, v147
	s_waitcnt lgkmcnt(1)
	v_cvt_pk_bf16_f32 v154, v148, v149
	s_waitcnt lgkmcnt(0)
	v_cvt_pk_bf16_f32 v155, v150, v151
	s_mov_b64 s[6:7], s[60:61]
	global_store_dwordx4 v249, v[152:155], s[6:7] sc1
	ds_read2_b32 v[144:145], v206 offset0:8 offset1:41
	ds_read2_b32 v[146:147], v206 offset0:74 offset1:107
	ds_read2_b32 v[148:149], v206 offset0:140 offset1:173
	ds_read2_b32 v[150:151], v206 offset0:206 offset1:239
	s_waitcnt lgkmcnt(3)
	v_cvt_pk_bf16_f32 v156, v144, v145
	s_waitcnt lgkmcnt(2)
	v_cvt_pk_bf16_f32 v157, v146, v147
	s_waitcnt lgkmcnt(1)
	v_cvt_pk_bf16_f32 v158, v148, v149
	s_waitcnt lgkmcnt(0)
	v_cvt_pk_bf16_f32 v159, v150, v151
	s_add_u32 s6, s6, 0x8000
	s_addc_u32 s7, s7, 0
	global_store_dwordx4 v249, v[156:159], s[6:7] sc1
	ds_read2_b32 v[144:145], v206 offset0:16 offset1:49
	ds_read2_b32 v[146:147], v206 offset0:82 offset1:115
	ds_read2_b32 v[148:149], v206 offset0:148 offset1:181
	ds_read2_b32 v[150:151], v206 offset0:214 offset1:247
	s_waitcnt lgkmcnt(3)
	v_cvt_pk_bf16_f32 v152, v144, v145
	s_waitcnt lgkmcnt(2)
	v_cvt_pk_bf16_f32 v153, v146, v147
	s_waitcnt lgkmcnt(1)
	v_cvt_pk_bf16_f32 v154, v148, v149
	s_waitcnt lgkmcnt(0)
	v_cvt_pk_bf16_f32 v155, v150, v151
	s_add_u32 s6, s6, 0x8000
	s_addc_u32 s7, s7, 0
	global_store_dwordx4 v249, v[152:155], s[6:7] sc1
	ds_read2_b32 v[144:145], v206 offset0:24 offset1:57
	ds_read2_b32 v[146:147], v206 offset0:90 offset1:123
	ds_read2_b32 v[148:149], v206 offset0:156 offset1:189
	ds_read2_b32 v[150:151], v206 offset0:222 offset1:255
	s_waitcnt lgkmcnt(3)
	v_cvt_pk_bf16_f32 v156, v144, v145
	s_waitcnt lgkmcnt(2)
	v_cvt_pk_bf16_f32 v157, v146, v147
	s_waitcnt lgkmcnt(1)
	v_cvt_pk_bf16_f32 v158, v148, v149
	s_waitcnt lgkmcnt(0)
	v_cvt_pk_bf16_f32 v159, v150, v151
	s_add_u32 s6, s6, 0x8000
	s_addc_u32 s7, s7, 0
	global_store_dwordx4 v249, v[156:159], s[6:7] sc1
	s_cmp_eq_u32 s52, 0
	s_cbranch_scc1 .Ltail_end
	s_sub_u32 s52, s52, 1
	s_branch .Ltail_loop
